# MLA loop hand-rescheduled (K frags upfront, V^T key-permuted LDS layout with b128 reads), FOX early-exit ncl load hoisted
# speedup vs baseline: 1.0265x; 1.0265x over previous
;     ...
;         if (MODE == 0 && DESC) {
;             const float ncl = (kt > 0) ? cdec[64 * kt - 1] : 0.f;
;             const bool live = !(qn + ncl - m < -152.f);
.LBB0_748:
	v_mov_b32_e32 v231, 0
	s_cmp_lt_i32 s27, 1
	s_cbranch_scc1 .Lfox_ncl_skip
	s_lshl_b32 s18, s14, 2
	s_add_u32 s18, s12, s18
	s_addc_u32 s19, s13, 0
	global_load_dword v231, v1, s[18:19] offset:252

;     ...
;         if (MODE == 0 && DESC) {
;             const float ncl = (kt > 0) ? cdec[64 * kt - 1] : 0.f;
;             const bool live = !(qn + ncl - m < -152.f);
.LBB0_757:
	s_or_b64 exec, exec, s[18:19]
	s_branch .LBB0_761

;     ...
;         if (MODE == 0 && DESC) {
;             const float ncl = (kt > 0) ? cdec[64 * kt - 1] : 0.f;
;             const bool live = !(qn + ncl - m < -152.f);
;             const int done = (__builtin_amdgcn_ballot_w64(live) == 0) ? 1 : 0;
;             if (lane == 0) ((int*)(smem0 + SMEM_FLAG))[(it & 1) * 8 + hf * 4 + w] = done;
;         }
;         if (it + 1 < ntiles) st_tile(buf ^ 1);
.LBB0_761:
	s_waitcnt vmcnt(0) lgkmcnt(0)
	v_add_f32_e32 v34, v132, v231
	v_sub_f32_e32 v34, v34, v139
	s_mov_b32 s18, 0xc3180000
	v_cmp_ngt_f32_e32 vcc, s18, v34
	s_and_saveexec_b64 s[18:19], s[8:9]
	s_cmp_eq_u64 vcc, 0
	s_cselect_b64 s[20:21], -1, 0
	v_cndmask_b32_e64 v34, 0, 1, s[20:21]
	v_lshl_add_u32 v35, s15, 5, v134
	ds_write_b32 v35, v34
	s_or_b64 exec, exec, s[18:19]
	s_andn2_b64 vcc, exec, s[16:17]
	s_cbranch_vccnz .LBB0_767
	s_xor_b32 s15, s15, 1
	s_mulk_i32 s15, 0x5900
	s_add_i32 s15, s33, s15
	v_add3_u32 v34, s15, v113, v137
	ds_write_b128 v34, v[82:85]
	v_add3_u32 v34, s15, v125, v138
	ds_write_b128 v34, v[86:89]
	v_add3_u32 v34, s15, v126, v127
	ds_write_b128 v34, v[90:93] offset:13312
	v_add3_u32 v34, s15, v128, v127
	ds_write_b128 v34, v[94:97] offset:13312
	s_and_saveexec_b64 s[16:17], s[4:5]
	v_lshl_add_u32 v34, v110, 2, s15
	ds_write_b128 v34, v[98:101] offset:22528
	s_or_b64 exec, exec, s[16:17]

; DI int tid_op() { int t = threadIdx.x & 255; asm volatile("" : "+v"(t)); return t; }
;     constexpr int KS = DQK + 8, NKS = DQK / 16, KCH = DQK / 8, NKL = 64 * KCH / 256;
;     const int tid = tid_op(), lane = tid & 63, w = tid >> 6, r = lane & 31, h = lane >> 5;
;     const int qidx = q0 + 32 * w + r;
;     bf16x8 qf[NKS];
; #pragma unroll
;     for (int s = 0; s < NKS; ++s) qf[s] = *(const bf16x8*)(Q + (size_t)(32 * w + r) * DQK + 16 * s + 8 * h);
;     float qn = 0.f;
;     if (MODE == 0 && DESC) {
; #pragma unroll
;         for (int s = 0; s < NKS; ++s)
; #pragma unroll
;             for (int j = 0; j < 8; ++j) { const float a = __uint_as_float(((unsigned)(unsigned short)qf[s][j]) << 16); qn += a * a; }
;         qn += xhalf_other(qn, h);
;         qn = sqrtf(qn) * kmax;
;     }
;     f32x16 o0, o1;
; #pragma unroll
;     for (int i = 0; i < 16; ++i) { o0[i] = 0.f; o1[i] = 0.f; }
;     float m = -INFINITY, lsum = 0.f, R = 1.f;
;     u32x4 rk[NKL], rv[2]; f32x4 rc = {0.f, 0.f, 0.f, 0.f};
;     const unsigned okk = (unsigned)(((tid / KCH) * DQK + (tid % KCH) * 8) * 2);
;     const unsigned ovv = (unsigned)(((tid >> 3) * ldv + (tid & 7) * 8) * 2), svv = (unsigned)(ldv * 64);
;     auto ld_tile = [&](int kt) {
;         const unsigned char* Kt = (const unsigned char*)(K + (size_t)(64 * kt) * DQK);
;         const unsigned char* Vt = (const unsigned char*)(VT + 64 * kt);
; #pragma unroll
;         for (int j = 0; j < NKL; ++j) rk[j] = *(const u32x4*)(Kt + (okk + j * 4096));
; #pragma unroll
;         for (int j = 0; j < 2; ++j) rv[j] = *(const u32x4*)(Vt + (ovv + j * svv));
;         if (cdec && tid < 16) rc = *(const f32x4*)(cdec + 64 * kt + 4 * tid);
;     };
;     auto st_tile = [&](int buf) {
;         bf16_t* sK = (bf16_t*)(smem + buf * ATT_BUF); bf16_t* sV = (bf16_t*)(smem + buf * ATT_BUF + 13312); float* sC = (float*)(smem + buf * ATT_BUF + 22528);
; #pragma unroll
;         for (int j = 0; j < NKL; ++j) { const int c = tid + 256 * j, row = c / KCH, kc = (c % KCH) * 8; *(u32x4*)(sK + row * KS + kc) = rk[j]; }
; #pragma unroll
;         for (int j = 0; j < 2; ++j) { const int c = tid + 256 * j, row = c >> 3, kc = (c & 7) * 8; *(u32x4*)(sV + row * LS + kc) = rv[j]; }
;         if (cdec && tid < 16) *(f32x4*)(sC + 4 * tid) = rc;
;     };
;     ld_tile(DESC ? ntiles - 1 : 0);
;     __syncthreads();
;     st_tile(0);
.LBB0_771:
	s_and_b64 vcc, exec, s[4:5]
	s_cbranch_vccz .LBB0_786
	s_lshl_b64 s[4:5], s[10:11], 13
	s_or_b32 s4, s4, s94
	s_mulk_i32 s5, 0xc0
	s_mul_hi_u32 s6, s4, 0xc0
	s_add_i32 s5, s6, s5
	s_mulk_i32 s4, 0xc0
	v_readlane_b32 s0, v254, 58
	s_add_u32 s6, s0, s4
	v_readlane_b32 s0, v254, 59
	v_mov_b32_e32 v8, v215
	s_addc_u32 s7, s0, s5
	s_mul_i32 s4, s10, 0x180000
	v_ashrrev_i32_e32 v9, 1, v8
	v_readlane_b32 s0, v254, 60
	v_bfe_u32 v121, v8, 5, 1
	v_bfi_b32 v110, s41, v9, v8
	v_mov_b64_e32 v[2:3], s[6:7]
	s_mul_hi_u32 s5, s10, 0x180000
	s_add_u32 s4, s0, s4
	v_readlane_b32 s0, v254, 61
	v_mad_i64_i32 v[2:3], s[6:7], v110, s85, v[2:3]
	v_lshlrev_b32_e32 v0, 4, v121
	s_addc_u32 s5, s0, s5
	v_lshl_add_u64 v[2:3], v[2:3], 0, v[0:1]
	v_lshlrev_b32_e32 v0, 4, v8
	v_lshl_add_u64 v[4:5], s[4:5], 0, v[0:1]
	v_add_u32_e32 v112, 0x1000, v0
	v_mov_b32_e32 v113, v1
	v_lshl_add_u64 v[6:7], s[4:5], 0, v[112:113]
	flat_load_dwordx4 v[66:69], v[4:5]
	flat_load_dwordx4 v[70:73], v[6:7]
	v_add_u32_e32 v114, 0x2000, v0
	v_mov_b32_e32 v115, v1
	s_lshl_b64 s[6:7], s[10:11], 20
	v_lshl_add_u64 v[4:5], s[4:5], 0, v[114:115]
	v_readlane_b32 s0, v254, 62
	flat_load_dwordx4 v[74:77], v[4:5]
	s_add_u32 s6, s0, s6
	v_readlane_b32 s0, v254, 63
	s_addc_u32 s7, s0, s7
	v_lshlrev_b32_e32 v4, 11, v8
	v_and_b32_e32 v5, 0x70, v0
	s_movk_i32 s0, 0xc000
	v_and_or_b32 v116, v4, s0, v5
	v_mov_b32_e32 v117, v1
	v_lshl_add_u64 v[4:5], s[6:7], 0, v[116:117]
	flat_load_dwordx4 v[78:81], v[4:5]
	v_add_u32_e32 v118, 0x80000, v116
	v_mov_b32_e32 v119, v1
	v_lshl_add_u64 v[4:5], s[6:7], 0, v[118:119]
	flat_load_dwordx4 v[82:85], v[4:5]
	flat_load_dwordx4 v[86:89], v[2:3]
	flat_load_dwordx4 v[90:93], v[2:3] offset:32
	flat_load_dwordx4 v[94:97], v[2:3] offset:64
	flat_load_dwordx4 v[98:101], v[2:3] offset:96
	flat_load_dwordx4 v[102:105], v[2:3] offset:128
	flat_load_dwordx4 v[106:109], v[2:3] offset:160
	s_mov_b32 s0, 0x2aaaaaab
	v_mul_hi_i32 v5, v8, s0
	v_add_u32_e32 v6, 0x100, v8
	v_add_u32_e32 v7, 0x200, v8
	v_lshrrev_b32_e32 v11, 31, v5
	v_ashrrev_i32_e32 v5, 1, v5
	v_mul_hi_i32 v12, v6, s0
	v_and_b32_e32 v9, 0xffffffe0, v9
	v_mul_hi_i32 v13, v7, s0
	v_add_u32_e32 v2, v5, v11
	v_lshrrev_b32_e32 v3, 31, v12
	v_ashrrev_i32_e32 v5, 1, v12
	s_movk_i32 s0, 0x68
	v_add_u32_e32 v125, s94, v9
	v_lshrrev_b32_e32 v9, 31, v13
	v_ashrrev_i32_e32 v11, 1, v13
	v_mul_lo_u32 v12, v2, 12
	v_mul_lo_u32 v2, v2, s0
	v_add_u32_e32 v3, v5, v3
	v_add_u32_e32 v5, v11, v9
	v_sub_u32_e32 v9, v8, v12
	v_lshlrev_b32_e32 v127, 1, v2
	v_mul_lo_u32 v2, v3, 12
	v_mul_lo_u32 v3, v3, s0
	v_lshlrev_b32_e32 v11, 3, v9
	v_lshlrev_b32_e32 v9, 4, v9
	v_sub_u32_e32 v2, v6, v2
	v_lshlrev_b32_e32 v128, 1, v3
	v_add3_u32 v3, s33, v127, v9
	v_lshlrev_b32_e32 v9, 3, v2
	v_lshlrev_b32_e32 v2, 4, v2
	v_add3_u32 v2, s33, v128, v2
	s_waitcnt lgkmcnt(0)
	s_barrier
	v_and_b32_e32 v4, 31, v8
	v_lshlrev_b32_e32 v10, 3, v121
	s_waitcnt vmcnt(0)
	ds_write_b128 v3, v[66:69]
	ds_write_b128 v2, v[70:73]
	v_mul_lo_u32 v2, v5, 12
	v_sub_u32_e32 v2, v7, v2
	v_mul_lo_u32 v5, v5, s0
	v_lshlrev_b32_e32 v3, 3, v2
	v_lshlrev_b32_e32 v129, 1, v5
	v_lshlrev_b32_e32 v2, 4, v2
	v_add3_u32 v2, s33, v129, v2
	ds_write_b128 v2, v[74:77]
	v_lshrrev_b32_e32 v2, 3, v8
	v_lshlrev_b32_e32 v5, 3, v8
	s_movk_i32 s0, 0x48
	v_and_b32_e32 v5, 56, v5
	v_mul_lo_u32 v2, v2, s0
	v_lshlrev_b32_e32 v130, 1, v2
	v_lshlrev_b32_e32 v131, 1, v5
	v_and_b32_e32 v217, 1, v215
	v_lshlrev_b32_e32 v217, 3, v217
	v_sub_u32_e32 v217, v131, v217
	v_add_u32_e32 v217, 0x3400, v217
	v_add3_u32 v2, s33, v130, v217
	ds_write2_b64 v2, v[78:79], v[80:81] offset1:2
	v_lshrrev_b32_e32 v2, 3, v6
	v_mul_lo_u32 v2, v2, s0
	v_lshlrev_b32_e32 v132, 1, v2
	v_add3_u32 v2, s33, v132, v217
	v_mov_b32_e32 v18, v1
	v_mov_b32_e32 v19, v1
	v_or_b32_e32 v126, v125, v4
	ds_write2_b64 v2, v[82:83], v[84:85] offset1:2
	v_mul_u32_u24_e32 v134, 0xd0, v4
	v_mul_u32_u24_e32 v136, 0x90, v4
	v_mov_b32_e32 v20, v1
	v_mov_b32_e32 v21, v1
	v_mov_b32_e32 v22, v1
	v_mov_b32_e32 v23, v1
	v_mov_b32_e32 v24, v1
	v_mov_b32_e32 v25, v1
	v_mov_b32_e32 v26, v1
	v_mov_b32_e32 v27, v1
	v_mov_b32_e32 v28, v1
	v_mov_b32_e32 v29, v1
	v_mov_b32_e32 v30, v1
	v_mov_b32_e32 v31, v1
	v_mov_b32_e32 v32, v1
	v_mov_b32_e32 v33, v1
	v_lshlrev_b32_e32 v137, 1, v10
	v_lshlrev_b32_e32 v138, 1, v11
	v_lshlrev_b32_e32 v139, 1, v9
	v_lshlrev_b32_e32 v140, 1, v3
	v_mov_b64_e32 v[2:3], v[18:19]
	s_mov_b32 s95, s49
	v_ashrrev_i32_e32 v111, 31, v110
	v_or_b32_e32 v133, 31, v125
	v_lshlrev_b32_e32 v123, 2, v121
	s_mov_b32 s16, 0
	v_mov_b32_e32 v135, 0
	v_mov_b32_e32 v122, 0xff800000
	s_mov_b32 s12, 0
	v_mov_b64_e32 v[4:5], v[20:21]
	v_mov_b64_e32 v[6:7], v[22:23]
	v_mov_b64_e32 v[8:9], v[24:25]
	v_mov_b64_e32 v[10:11], v[26:27]
	v_mov_b64_e32 v[12:13], v[28:29]
	v_mov_b64_e32 v[14:15], v[30:31]
	v_mov_b64_e32 v[16:17], v[32:33]

; #define MFMA32(a, b, c) __builtin_amdgcn_mfma_f32_32x32x16_bf16((a), (b), (c), 0, 0, 0)
;     ...
;         const bf16_t* sK = (const bf16_t*)(smem + buf * ATT_BUF); const bf16_t* sV = (const bf16_t*)(smem + buf * ATT_BUF + 13312);
;         const float* sC = (const float*)(smem + buf * ATT_BUF + 22528);
;         bool active = true;
;         if (MODE == 0) active = (64 * kt <= q0 + 32 * w + 31);
;         if (MODE == 1) active = (64 * kt < q0 + 32 * w + 31);
;         if (active) {
;             f32x16 sc[2];
; #pragma unroll
;             for (int i = 0; i < 16; ++i) { sc[0][i] = 0.f; sc[1][i] = 0.f; }
; #pragma unroll
;             for (int s = 0; s < NKS; ++s) {
;                 const bf16x8 k0 = *(const bf16x8*)(sK + r * KS + 16 * s + 8 * h), k1 = *(const bf16x8*)(sK + (32 + r) * KS + 16 * s + 8 * h);
;                 sc[0] = MFMA32(k0, qf[s], sc[0]);
;                 sc[1] = MFMA32(k1, qf[s], sc[1]);
;             }
;     ...
;                 if (MODE == 0 && (64 * kt + 63 > q0 + 32 * w)) {
; #pragma unroll
;                     for (int mt = 0; mt < 2; ++mt)
; #pragma unroll
;                         for (int qd = 0; qd < 4; ++qd)
; #pragma unroll
;                             for (int e = 0; e < 4; ++e)
;                                 if (64 * kt + 32 * mt + 8 * qd + 4 * h + e > qidx) s4[mt][qd][e] = -INFINITY;
;                 }
.LBB0_775:
	s_and_b32 s18, s12, 1
	v_cmp_le_i32_e32 vcc, s16, v133
	s_waitcnt lgkmcnt(0)
	s_barrier
	s_and_saveexec_b64 s[12:13], vcc
	s_cbranch_execz .LBB0_781
	s_mul_i32 s14, s18, 0x5900
	s_add_i32 s19, s33, s14
	v_add3_u32 v216, s19, v134, v137
	v_lshlrev_b32_e32 v154, 2, v123
	ds_read_b128 v[176:179], v216
	ds_read_b128 v[180:183], v216 offset:6656
	v_add3_u32 v212, s19, v136, v154
	s_add_i32 s14, s16, 63
	ds_read_b128 v[184:187], v216 offset:32
	ds_read_b128 v[188:191], v216 offset:6688
	v_cmp_gt_i32_e32 vcc, s14, v125
	ds_read_b128 v[192:195], v216 offset:64
	ds_read_b128 v[196:199], v216 offset:6720
	ds_read_b128 v[200:203], v216 offset:96
	ds_read_b128 v[204:207], v216 offset:6752
	ds_read_b128 v[208:211], v216 offset:128
	ds_read_b128 v[232:235], v216 offset:6784
	ds_read_b128 v[236:239], v216 offset:160
	ds_read_b128 v[240:243], v216 offset:6816
	s_waitcnt lgkmcnt(10)
	v_mfma_f32_32x32x16_bf16 v[50:65], v[176:179], v[86:89], 0
	v_mfma_f32_32x32x16_bf16 v[34:49], v[180:183], v[86:89], 0
	s_waitcnt lgkmcnt(8)
	v_mfma_f32_32x32x16_bf16 v[50:65], v[184:187], v[90:93], v[50:65]
	v_mfma_f32_32x32x16_bf16 v[34:49], v[188:191], v[90:93], v[34:49]
	s_waitcnt lgkmcnt(6)
	v_mfma_f32_32x32x16_bf16 v[50:65], v[192:195], v[94:97], v[50:65]
	v_mfma_f32_32x32x16_bf16 v[34:49], v[196:199], v[94:97], v[34:49]
	s_waitcnt lgkmcnt(4)
	v_mfma_f32_32x32x16_bf16 v[50:65], v[200:203], v[98:101], v[50:65]
	v_mfma_f32_32x32x16_bf16 v[34:49], v[204:207], v[98:101], v[34:49]
	s_waitcnt lgkmcnt(2)
	v_mfma_f32_32x32x16_bf16 v[50:65], v[208:211], v[102:105], v[50:65]
	v_mfma_f32_32x32x16_bf16 v[34:49], v[232:235], v[102:105], v[34:49]
	s_waitcnt lgkmcnt(0)
	v_mfma_f32_32x32x16_bf16 v[50:65], v[236:239], v[106:109], v[50:65]
	v_mfma_f32_32x32x16_bf16 v[34:49], v[240:243], v[106:109], v[34:49]
	ds_read_b128 v[176:179], v212 offset:13312
	ds_read_b128 v[180:183], v212 offset:17920
	ds_read_b128 v[184:187], v212 offset:13344
	ds_read_b128 v[188:191], v212 offset:17952
	ds_read_b128 v[192:195], v212 offset:13376
	ds_read_b128 v[196:199], v212 offset:17984
	ds_read_b128 v[200:203], v212 offset:13408
	ds_read_b128 v[204:207], v212 offset:18016
	s_and_saveexec_b64 s[14:15], vcc
	s_cbranch_execz .LBB0_778
	v_add_u32_e32 v141, s16, v123
	v_mov_b32_e32 v120, s68
	v_cmp_gt_i32_e32 vcc, v141, v126
	v_add_u32_e32 v142, 8, v141
	s_nop 2
	v_cndmask_b32_e32 v120, v50, v120, vcc
	v_cmp_lt_i32_e32 vcc, v141, v126
	s_nop 1
	v_cndmask_b32_e32 v50, v120, v50, vcc
	v_add_u32_e32 v120, 2, v141
	v_cndmask_b32_e32 v51, v228, v51, vcc
	v_cmp_le_i32_e32 vcc, v120, v126
	v_add_u32_e32 v120, 3, v141
	s_nop 0
	v_cndmask_b32_e32 v52, v228, v52, vcc
	v_cmp_le_i32_e32 vcc, v120, v126
	v_mov_b32_e32 v120, s68
	s_nop 0
	v_cndmask_b32_e32 v53, v228, v53, vcc
	v_cmp_gt_i32_e32 vcc, v142, v126
	v_add_u32_e32 v142, 16, v141
	s_nop 0
	v_cndmask_b32_e32 v54, v54, v120, vcc
	v_add_u32_e32 v120, 9, v141
	v_cmp_le_i32_e32 vcc, v120, v126
	v_add_u32_e32 v120, 10, v141
	s_nop 0
	v_cndmask_b32_e32 v55, v228, v55, vcc
	v_cmp_le_i32_e32 vcc, v120, v126
	v_add_u32_e32 v120, 11, v141
	s_nop 0
	v_cndmask_b32_e32 v56, v228, v56, vcc
	v_cmp_le_i32_e32 vcc, v120, v126
	v_mov_b32_e32 v120, s68
	s_nop 0
	v_cndmask_b32_e32 v57, v228, v57, vcc
	v_cmp_gt_i32_e32 vcc, v142, v126
	v_add_u32_e32 v142, 24, v141
	s_nop 0
	v_cndmask_b32_e32 v58, v58, v120, vcc
	v_add_u32_e32 v120, 17, v141
	v_cmp_le_i32_e32 vcc, v120, v126
	v_add_u32_e32 v120, 18, v141
	s_nop 0
	v_cndmask_b32_e32 v59, v228, v59, vcc
	v_cmp_le_i32_e32 vcc, v120, v126
	v_add_u32_e32 v120, 19, v141
	s_nop 0
	v_cndmask_b32_e32 v60, v228, v60, vcc
	v_cmp_le_i32_e32 vcc, v120, v126
	v_mov_b32_e32 v120, s68
	s_nop 0
	v_cndmask_b32_e32 v61, v228, v61, vcc
	v_cmp_gt_i32_e32 vcc, v142, v126
	v_add_u32_e32 v142, 32, v141
	s_nop 0
	v_cndmask_b32_e32 v62, v62, v120, vcc
	v_add_u32_e32 v120, 25, v141
	v_cmp_le_i32_e32 vcc, v120, v126
	v_add_u32_e32 v120, 26, v141
	s_nop 0
	v_cndmask_b32_e32 v63, v228, v63, vcc
	v_cmp_le_i32_e32 vcc, v120, v126
	v_add_u32_e32 v120, 27, v141
	s_nop 0
	v_cndmask_b32_e32 v64, v228, v64, vcc
	v_cmp_le_i32_e32 vcc, v120, v126
	v_mov_b32_e32 v120, s68
	s_nop 0
	v_cndmask_b32_e32 v65, v228, v65, vcc
	v_cmp_gt_i32_e32 vcc, v142, v126
	v_add_u32_e32 v142, 40, v141
	s_nop 0
	v_cndmask_b32_e32 v34, v34, v120, vcc
	v_add_u32_e32 v120, 33, v141
	v_cmp_le_i32_e32 vcc, v120, v126
	v_add_u32_e32 v120, 34, v141
	s_nop 0
	v_cndmask_b32_e32 v35, v228, v35, vcc
	v_cmp_le_i32_e32 vcc, v120, v126
	v_add_u32_e32 v120, 35, v141
	s_nop 0
	v_cndmask_b32_e32 v36, v228, v36, vcc
	v_cmp_le_i32_e32 vcc, v120, v126
	v_mov_b32_e32 v120, s68
	s_nop 0
	v_cndmask_b32_e32 v37, v228, v37, vcc
	v_cmp_gt_i32_e32 vcc, v142, v126
	v_add_u32_e32 v142, 48, v141
	s_nop 0
	v_cndmask_b32_e32 v38, v38, v120, vcc
	v_add_u32_e32 v120, 41, v141
	v_cmp_le_i32_e32 vcc, v120, v126
	v_add_u32_e32 v120, 42, v141
	s_nop 0
	v_cndmask_b32_e32 v39, v228, v39, vcc
	v_cmp_le_i32_e32 vcc, v120, v126
	v_add_u32_e32 v120, 43, v141
	s_nop 0
	v_cndmask_b32_e32 v40, v228, v40, vcc
	v_cmp_le_i32_e32 vcc, v120, v126
	v_mov_b32_e32 v120, s68
	s_nop 0
	v_cndmask_b32_e32 v41, v228, v41, vcc
	v_cmp_gt_i32_e32 vcc, v142, v126
	v_add_u32_e32 v142, 56, v141
	s_nop 0
	v_cndmask_b32_e32 v42, v42, v120, vcc
	v_add_u32_e32 v120, 49, v141
	v_cmp_le_i32_e32 vcc, v120, v126
	v_add_u32_e32 v120, 50, v141
	s_nop 0
	v_cndmask_b32_e32 v43, v228, v43, vcc
	v_cmp_le_i32_e32 vcc, v120, v126
	v_add_u32_e32 v120, 51, v141
	s_nop 0
	v_cndmask_b32_e32 v44, v228, v44, vcc
	v_cmp_le_i32_e32 vcc, v120, v126
	v_mov_b32_e32 v120, s68
	s_nop 0
	v_cndmask_b32_e32 v45, v228, v45, vcc
	v_cmp_gt_i32_e32 vcc, v142, v126
	s_nop 1
	v_cndmask_b32_e32 v46, v46, v120, vcc
	v_add_u32_e32 v120, 57, v141
	v_cmp_le_i32_e32 vcc, v120, v126
	v_add_u32_e32 v120, 58, v141
	s_nop 0
	v_cndmask_b32_e32 v47, v228, v47, vcc
	v_cmp_le_i32_e32 vcc, v120, v126
	v_add_u32_e32 v120, 59, v141
	s_nop 0
	v_cndmask_b32_e32 v48, v228, v48, vcc
	v_cmp_le_i32_e32 vcc, v120, v126
	s_nop 1
	v_cndmask_b32_e32 v49, v228, v49, vcc
;     ...
;     auto st_tile = [&](int buf) {
;         bf16_t* sK = (bf16_t*)(smem + buf * ATT_BUF); bf16_t* sV = (bf16_t*)(smem + buf * ATT_BUF + 13312); float* sC = (float*)(smem + buf * ATT_BUF + 22528);
; #pragma unroll
;     ...
;                 float mx = fmaxf(s4[0][0].x, s4[1][0].x);
; #pragma unroll
;                 for (int qd = 0; qd < 4; ++qd) {
;                     mx = fmaxf(fmaxf(mx, s4[0][qd].y), s4[1][qd].y);
;                     mx = fmaxf(fmaxf(mx, s4[0][qd].z), s4[1][qd].z);
;                     mx = fmaxf(fmaxf(mx, s4[0][qd].w), s4[1][qd].w);
;                     if (qd < 3) mx = fmaxf(fmaxf(mx, s4[0][qd + 1].x), s4[1][qd + 1].x);
;                 }
;                 mx = xhalf_max(mx);
;                 const float mn = fmaxf(m, mx), alpha = fexp2(m - mn);
;                 m = mn;
;                 f32x4 ps4 = {0.f, 0.f, 0.f, 0.f};
;                 const float nmn = -mn;
;                 const f32x4 nm4 = {nmn, nmn, nmn, nmn};
;                 if (__builtin_amdgcn_ballot_w64(alpha != 1.f) != 0) { o0 *= alpha; o1 *= alpha; }
; #pragma unroll
;                 for (int s2 = 0; s2 < 4; ++s2) {
;                     const int mt = s2 >> 1, s = s2 & 1;
;                     f32x4 da = s4[mt][2 * s] + nm4, db = s4[mt][2 * s + 1] + nm4;
;                     da.x = fexp2(da.x); da.y = fexp2(da.y); da.z = fexp2(da.z); da.w = fexp2(da.w);
;                     db.x = fexp2(db.x); db.y = fexp2(db.y); db.z = fexp2(db.z); db.w = fexp2(db.w);
;                     ps4 += da; ps4 += db;
;                     u32x4 pp;
;                     pp.x = pk2(da.x, da.y); pp.y = pk2(da.z, da.w); pp.z = pk2(db.x, db.y); pp.w = pk2(db.z, db.w);
;                     const bf16x8 pfr = __builtin_bit_cast(bf16x8, pp);
;                     const s16x4 a0 = *(const s16x4*)(sV + r * LS + 16 * s2 + 4 * h), a1 = *(const s16x4*)(sV + r * LS + 16 * s2 + 8 + 4 * h);
;                     const s16x4 b0 = *(const s16x4*)(sV + (32 + r) * LS + 16 * s2 + 4 * h), b1 = *(const s16x4*)(sV + (32 + r) * LS + 16 * s2 + 8 + 4 * h);
;                     const bf16x8 v0 = __builtin_shufflevector(a0, a1, 0, 1, 2, 3, 4, 5, 6, 7), v1 = __builtin_shufflevector(b0, b1, 0, 1, 2, 3, 4, 5, 6, 7);
;                     o0 = MFMA32(v0, pfr, o0);
;                     o1 = MFMA32(v1, pfr, o1);
;                 }
;                 lsum = lsum * alpha + ((ps4.x + ps4.y) + (ps4.z + ps4.w));
.LBB0_778:
	s_or_b64 exec, exec, s[14:15]
	s_nop 1
	v_max3_f32 v120, v50, v51, v52
	v_max3_f32 v141, v53, v54, v55
	v_max3_f32 v154, v56, v57, v58
	v_max3_f32 v248, v59, v60, v61
	v_max3_f32 v120, v120, v62, v63
	v_max3_f32 v141, v141, v64, v65
	v_max3_f32 v154, v154, v34, v35
	v_max3_f32 v248, v248, v36, v37
	v_max3_f32 v120, v120, v38, v39
	v_max3_f32 v141, v141, v40, v41
	v_max3_f32 v154, v154, v42, v43
	v_max3_f32 v248, v248, v44, v45
	v_max3_f32 v120, v120, v46, v47
	v_max3_f32 v141, v141, v48, v49
	v_max3_f32 v120, v120, v141, v154
	v_max_f32_e32 v120, v120, v248
	v_mov_b32_e32 v141, v120
	s_nop 1
	v_permlane32_swap_b32_e32 v120, v141
	v_max3_f32 v120, v122, v120, v141
	v_sub_f32_e32 v122, v122, v120
	v_exp_f32_e32 v122, v122
	s_nop 0
	v_cmp_neq_f32_e32 vcc, 1.0, v122
	s_cbranch_vccz .LBB0_780
	v_pk_mul_f32 v[32:33], v[32:33], v[122:123] op_sel_hi:[1,0]
	v_pk_mul_f32 v[30:31], v[30:31], v[122:123] op_sel_hi:[1,0]
	v_pk_mul_f32 v[28:29], v[28:29], v[122:123] op_sel_hi:[1,0]
	v_pk_mul_f32 v[26:27], v[26:27], v[122:123] op_sel_hi:[1,0]
	v_pk_mul_f32 v[24:25], v[24:25], v[122:123] op_sel_hi:[1,0]
	v_pk_mul_f32 v[22:23], v[22:23], v[122:123] op_sel_hi:[1,0]
	v_pk_mul_f32 v[20:21], v[20:21], v[122:123] op_sel_hi:[1,0]
	v_pk_mul_f32 v[18:19], v[18:19], v[122:123] op_sel_hi:[1,0]
	v_pk_mul_f32 v[16:17], v[16:17], v[122:123] op_sel_hi:[1,0]
	v_pk_mul_f32 v[14:15], v[14:15], v[122:123] op_sel_hi:[1,0]
	v_pk_mul_f32 v[12:13], v[12:13], v[122:123] op_sel_hi:[1,0]
	v_pk_mul_f32 v[10:11], v[10:11], v[122:123] op_sel_hi:[1,0]
	v_pk_mul_f32 v[8:9], v[8:9], v[122:123] op_sel_hi:[1,0]
	v_pk_mul_f32 v[6:7], v[6:7], v[122:123] op_sel_hi:[1,0]
	v_pk_mul_f32 v[4:5], v[4:5], v[122:123] op_sel_hi:[1,0]
	v_pk_mul_f32 v[2:3], v[2:3], v[122:123] op_sel_hi:[1,0]
.LBB0_780:
	v_sub_f32_e32 v50, v50, v120
	v_sub_f32_e32 v51, v51, v120
	v_sub_f32_e32 v52, v52, v120
	v_sub_f32_e32 v53, v53, v120
	v_sub_f32_e32 v54, v54, v120
	v_sub_f32_e32 v55, v55, v120
	v_sub_f32_e32 v56, v56, v120
	v_sub_f32_e32 v57, v57, v120
	v_exp_f32_e32 v50, v50
	v_exp_f32_e32 v51, v51
	v_exp_f32_e32 v52, v52
	v_exp_f32_e32 v53, v53
	v_exp_f32_e32 v54, v54
	v_exp_f32_e32 v55, v55
	v_exp_f32_e32 v56, v56
	v_exp_f32_e32 v57, v57
	v_cvt_pk_bf16_f32 v142, v50, v51
	v_cvt_pk_bf16_f32 v143, v52, v53
	v_cvt_pk_bf16_f32 v144, v54, v55
	v_cvt_pk_bf16_f32 v145, v56, v57
	s_waitcnt lgkmcnt(0)
	v_sub_f32_e32 v58, v58, v120
	v_sub_f32_e32 v59, v59, v120
	v_sub_f32_e32 v60, v60, v120
	v_sub_f32_e32 v61, v61, v120
	v_sub_f32_e32 v62, v62, v120
	v_sub_f32_e32 v63, v63, v120
	v_sub_f32_e32 v64, v64, v120
	v_sub_f32_e32 v65, v65, v120
	v_mfma_f32_32x32x16_bf16 v[18:33], v[176:179], v[142:145], v[18:33]
	v_exp_f32_e32 v58, v58
	v_exp_f32_e32 v59, v59
	v_exp_f32_e32 v60, v60
	v_exp_f32_e32 v61, v61
	v_mfma_f32_32x32x16_bf16 v[2:17], v[180:183], v[142:145], v[2:17]
	v_exp_f32_e32 v62, v62
	v_exp_f32_e32 v63, v63
	v_exp_f32_e32 v64, v64
	v_exp_f32_e32 v65, v65
	v_add_f32_e32 v248, v50, v51
	v_add_f32_e32 v249, v52, v53
	v_add_f32_e32 v250, v54, v55
	v_add_f32_e32 v251, v56, v57
	v_add_f32_e32 v248, v248, v249
	v_add_f32_e32 v250, v250, v251
	v_add_f32_e32 v230, v248, v250
	v_cvt_pk_bf16_f32 v146, v58, v59
	v_cvt_pk_bf16_f32 v147, v60, v61
	v_cvt_pk_bf16_f32 v148, v62, v63
	v_cvt_pk_bf16_f32 v149, v64, v65
	v_sub_f32_e32 v34, v34, v120
	v_sub_f32_e32 v35, v35, v120
	v_sub_f32_e32 v36, v36, v120
	v_sub_f32_e32 v37, v37, v120
	v_sub_f32_e32 v38, v38, v120
	v_sub_f32_e32 v39, v39, v120
	v_sub_f32_e32 v40, v40, v120
	v_sub_f32_e32 v41, v41, v120
	v_mfma_f32_32x32x16_bf16 v[18:33], v[184:187], v[146:149], v[18:33]
	v_exp_f32_e32 v34, v34
	v_exp_f32_e32 v35, v35
	v_exp_f32_e32 v36, v36
	v_exp_f32_e32 v37, v37
	v_mfma_f32_32x32x16_bf16 v[2:17], v[188:191], v[146:149], v[2:17]
	v_exp_f32_e32 v38, v38
	v_exp_f32_e32 v39, v39
	v_exp_f32_e32 v40, v40
	v_exp_f32_e32 v41, v41
	v_add_f32_e32 v248, v58, v59
	v_add_f32_e32 v249, v60, v61
	v_add_f32_e32 v250, v62, v63
	v_add_f32_e32 v251, v64, v65
	v_add_f32_e32 v248, v248, v249
	v_add_f32_e32 v250, v250, v251
	v_add_f32_e32 v248, v248, v250
	v_add_f32_e32 v230, v230, v248
	v_cvt_pk_bf16_f32 v150, v34, v35
	v_cvt_pk_bf16_f32 v151, v36, v37
	v_cvt_pk_bf16_f32 v152, v38, v39
	v_cvt_pk_bf16_f32 v153, v40, v41
	v_sub_f32_e32 v42, v42, v120
	v_sub_f32_e32 v43, v43, v120
	v_sub_f32_e32 v44, v44, v120
	v_sub_f32_e32 v45, v45, v120
	v_sub_f32_e32 v46, v46, v120
	v_sub_f32_e32 v47, v47, v120
	v_sub_f32_e32 v48, v48, v120
	v_sub_f32_e32 v49, v49, v120
	v_mfma_f32_32x32x16_bf16 v[18:33], v[192:195], v[150:153], v[18:33]
	v_exp_f32_e32 v42, v42
	v_exp_f32_e32 v43, v43
	v_exp_f32_e32 v44, v44
	v_exp_f32_e32 v45, v45
	v_mfma_f32_32x32x16_bf16 v[2:17], v[196:199], v[150:153], v[2:17]
	v_exp_f32_e32 v46, v46
	v_exp_f32_e32 v47, v47
	v_exp_f32_e32 v48, v48
	v_exp_f32_e32 v49, v49
	v_add_f32_e32 v248, v34, v35
	v_add_f32_e32 v249, v36, v37
	v_add_f32_e32 v250, v38, v39
	v_add_f32_e32 v251, v40, v41
	v_add_f32_e32 v248, v248, v249
	v_add_f32_e32 v250, v250, v251
	v_add_f32_e32 v248, v248, v250
	v_add_f32_e32 v230, v230, v248
	v_cvt_pk_bf16_f32 v244, v42, v43
	v_cvt_pk_bf16_f32 v245, v44, v45
	v_cvt_pk_bf16_f32 v246, v46, v47
	v_cvt_pk_bf16_f32 v247, v48, v49
	v_add_f32_e32 v248, v42, v43
	v_add_f32_e32 v249, v44, v45
	v_add_f32_e32 v250, v46, v47
	v_add_f32_e32 v251, v48, v49
	v_mfma_f32_32x32x16_bf16 v[18:33], v[200:203], v[244:247], v[18:33]
	v_mfma_f32_32x32x16_bf16 v[2:17], v[204:207], v[244:247], v[2:17]
	v_add_f32_e32 v248, v248, v249
	v_add_f32_e32 v250, v250, v251
	v_add_f32_e32 v248, v248, v250
	v_add_f32_e32 v230, v230, v248
	v_fma_f32 v135, v135, v122, v230
	v_mov_b32_e32 v122, v120
.LBB0_781:
	s_or_b64 exec, exec, s[12:13]
	s_andn2_b64 vcc, exec, s[8:9]
	s_cbranch_vccnz .LBB0_783
	s_xor_b32 s8, s18, 1
	s_mulk_i32 s8, 0x5900
	s_add_i32 s8, s33, s8
	v_add3_u32 v34, s8, v127, v138
	s_waitcnt vmcnt(0)
	ds_write_b128 v34, v[66:69]
	v_add3_u32 v34, s8, v128, v139
	ds_write_b128 v34, v[70:73]
	v_add3_u32 v34, s8, v129, v140
	ds_write_b128 v34, v[74:77]
	v_add3_u32 v34, s8, v130, v217
	ds_write2_b64 v34, v[78:79], v[80:81] offset1:2
	v_add3_u32 v34, s8, v132, v217
	ds_write2_b64 v34, v[82:83], v[84:85] offset1:2
